# MoBA routing-gate loop: block-mean LDS quads software-pipelined across the 8 groups of a trip; GLA pass-1 prefix sum: 16 LDS reads batched ahead of the serial add/write chain
# speedup vs baseline: 1.0049x; 1.0049x over previous
.LBB0_347:
	s_waitcnt lgkmcnt(0)
	s_or_b64 exec, exec, s[2:3]
	s_add_i32 s8, s8, 32
	s_cmpk_eq_i32 s8, 0x100
	v_lshl_add_u64 v[0:1], v[0:1], 0, 16
	s_cbranch_scc1 .LBB0_364

.Lmq_done:
	v_lshlrev_b32_e32 v12, 16, v36
	v_and_b32_e32 v13, 0xffff0000, v36
	v_lshlrev_b32_e32 v16, 16, v37
	v_and_b32_e32 v17, 0xffff0000, v37
	v_lshlrev_b32_e32 v8, 16, v38
	v_and_b32_e32 v9, 0xffff0000, v38
	v_lshlrev_b32_e32 v4, 16, v39
	v_and_b32_e32 v5, 0xffff0000, v39
	ds_read_b128 v[36:39], v31
	ds_read_b128 v[40:43], v31 offset:16
	s_and_saveexec_b64 s[2:3], s[38:39]
	s_cbranch_execnz .LBB0_356
	s_or_b64 exec, exec, s[2:3]
	s_and_saveexec_b64 s[2:3], s[40:41]
	s_cbranch_execnz .Lgk_in_1

.LBB0_356:
	ds_read_b128 v[224:227], v31 offset:512
	ds_read_b128 v[228:231], v31 offset:528
	s_waitcnt lgkmcnt(3)
	v_pk_mul_f32 v[36:37], v[36:37], v[12:13]
	s_nop 0
	v_add_f32_e32 v24, v24, v36
	v_add_f32_e32 v24, v24, v37
	v_pk_mul_f32 v[36:37], v[38:39], v[16:17]
	s_nop 0
	v_add_f32_e32 v24, v24, v36
	v_add_f32_e32 v24, v24, v37
	s_waitcnt lgkmcnt(2)
	v_pk_mul_f32 v[36:37], v[40:41], v[8:9]
	s_nop 0
	v_add_f32_e32 v24, v24, v36
	v_add_f32_e32 v24, v24, v37
	v_pk_mul_f32 v[36:37], v[42:43], v[4:5]
	s_nop 0
	v_add_f32_e32 v24, v24, v36
	v_add_f32_e32 v24, v24, v37
	s_or_b64 exec, exec, s[2:3]
	s_and_saveexec_b64 s[2:3], s[40:41]
	s_cbranch_execz .LBB0_350
.LBB0_357:
	ds_read_b128 v[36:39], v31 offset:1024
	ds_read_b128 v[40:43], v31 offset:1040
	s_waitcnt lgkmcnt(3)
	v_pk_mul_f32 v[224:225], v[224:225], v[12:13]
	s_nop 0
	v_add_f32_e32 v25, v25, v224
	v_add_f32_e32 v25, v25, v225
	v_pk_mul_f32 v[224:225], v[226:227], v[16:17]
	s_nop 0
	v_add_f32_e32 v25, v25, v224
	v_add_f32_e32 v25, v25, v225
	s_waitcnt lgkmcnt(2)
	v_pk_mul_f32 v[224:225], v[228:229], v[8:9]
	s_nop 0
	v_add_f32_e32 v25, v25, v224
	v_add_f32_e32 v25, v25, v225
	v_pk_mul_f32 v[224:225], v[230:231], v[4:5]
	s_nop 0
	v_add_f32_e32 v25, v25, v224
	v_add_f32_e32 v25, v25, v225
	s_or_b64 exec, exec, s[2:3]
	s_and_saveexec_b64 s[2:3], s[42:43]
	s_cbranch_execz .LBB0_351
.LBB0_358:
	ds_read_b128 v[224:227], v31 offset:1536
	ds_read_b128 v[228:231], v31 offset:1552
	s_waitcnt lgkmcnt(3)
	v_pk_mul_f32 v[36:37], v[36:37], v[12:13]
	s_nop 0
	v_add_f32_e32 v26, v26, v36
	v_add_f32_e32 v26, v26, v37
	v_pk_mul_f32 v[36:37], v[38:39], v[16:17]
	s_nop 0
	v_add_f32_e32 v26, v26, v36
	v_add_f32_e32 v26, v26, v37
	s_waitcnt lgkmcnt(2)
	v_pk_mul_f32 v[36:37], v[40:41], v[8:9]
	s_nop 0
	v_add_f32_e32 v26, v26, v36
	v_add_f32_e32 v26, v26, v37
	v_pk_mul_f32 v[36:37], v[42:43], v[4:5]
	s_nop 0
	v_add_f32_e32 v26, v26, v36
	v_add_f32_e32 v26, v26, v37
	s_or_b64 exec, exec, s[2:3]
	s_and_saveexec_b64 s[2:3], s[44:45]
	s_cbranch_execz .LBB0_352
.LBB0_359:
	ds_read_b128 v[36:39], v31 offset:2048
	ds_read_b128 v[40:43], v31 offset:2064
	s_waitcnt lgkmcnt(3)
	v_pk_mul_f32 v[224:225], v[224:225], v[12:13]
	s_nop 0
	v_add_f32_e32 v27, v27, v224
	v_add_f32_e32 v27, v27, v225
	v_pk_mul_f32 v[224:225], v[226:227], v[16:17]
	s_nop 0
	v_add_f32_e32 v27, v27, v224
	v_add_f32_e32 v27, v27, v225
	s_waitcnt lgkmcnt(2)
	v_pk_mul_f32 v[224:225], v[228:229], v[8:9]
	s_nop 0
	v_add_f32_e32 v27, v27, v224
	v_add_f32_e32 v27, v27, v225
	v_pk_mul_f32 v[224:225], v[230:231], v[4:5]
	s_nop 0
	v_add_f32_e32 v27, v27, v224
	v_add_f32_e32 v27, v27, v225
	s_or_b64 exec, exec, s[2:3]
	s_and_saveexec_b64 s[2:3], s[46:47]
	s_cbranch_execz .LBB0_353
.LBB0_360:
	ds_read_b128 v[224:227], v31 offset:2560
	ds_read_b128 v[228:231], v31 offset:2576
	s_waitcnt lgkmcnt(3)
	v_pk_mul_f32 v[36:37], v[36:37], v[12:13]
	s_nop 0
	v_add_f32_e32 v28, v28, v36
	v_add_f32_e32 v28, v28, v37
	v_pk_mul_f32 v[36:37], v[38:39], v[16:17]
	s_nop 0
	v_add_f32_e32 v28, v28, v36
	v_add_f32_e32 v28, v28, v37
	s_waitcnt lgkmcnt(2)
	v_pk_mul_f32 v[36:37], v[40:41], v[8:9]
	s_nop 0
	v_add_f32_e32 v28, v28, v36
	v_add_f32_e32 v28, v28, v37
	v_pk_mul_f32 v[36:37], v[42:43], v[4:5]
	s_nop 0
	v_add_f32_e32 v28, v28, v36
	v_add_f32_e32 v28, v28, v37
	s_or_b64 exec, exec, s[2:3]
	s_and_saveexec_b64 s[2:3], s[48:49]
	s_cbranch_execz .LBB0_354
.LBB0_361:
	ds_read_b128 v[36:39], v31 offset:3072
	ds_read_b128 v[40:43], v31 offset:3088
	s_waitcnt lgkmcnt(3)
	v_pk_mul_f32 v[224:225], v[224:225], v[12:13]
	s_nop 0
	v_add_f32_e32 v29, v29, v224
	v_add_f32_e32 v29, v29, v225
	v_pk_mul_f32 v[224:225], v[226:227], v[16:17]
	s_nop 0
	v_add_f32_e32 v29, v29, v224
	v_add_f32_e32 v29, v29, v225
	s_waitcnt lgkmcnt(2)
	v_pk_mul_f32 v[224:225], v[228:229], v[8:9]
	s_nop 0
	v_add_f32_e32 v29, v29, v224
	v_add_f32_e32 v29, v29, v225
	v_pk_mul_f32 v[224:225], v[230:231], v[4:5]
	s_nop 0
	v_add_f32_e32 v29, v29, v224
	v_add_f32_e32 v29, v29, v225
	s_or_b64 exec, exec, s[2:3]
	s_and_saveexec_b64 s[2:3], s[50:51]
	s_cbranch_execz .LBB0_355
.LBB0_362:
	ds_read_b128 v[224:227], v31 offset:3584
	ds_read_b128 v[228:231], v31 offset:3600
	s_waitcnt lgkmcnt(3)
	v_pk_mul_f32 v[36:37], v[36:37], v[12:13]
	s_nop 0
	v_add_f32_e32 v30, v30, v36
	v_add_f32_e32 v30, v30, v37
	v_pk_mul_f32 v[36:37], v[38:39], v[16:17]
	s_nop 0
	v_add_f32_e32 v30, v30, v36
	v_add_f32_e32 v30, v30, v37
	s_waitcnt lgkmcnt(2)
	v_pk_mul_f32 v[36:37], v[40:41], v[8:9]
	s_nop 0
	v_add_f32_e32 v30, v30, v36
	v_add_f32_e32 v30, v30, v37
	v_pk_mul_f32 v[36:37], v[42:43], v[4:5]
	s_nop 0
	v_add_f32_e32 v30, v30, v36
	v_add_f32_e32 v30, v30, v37
	s_or_b64 exec, exec, s[2:3]
	s_and_saveexec_b64 s[2:3], s[52:53]
	s_cbranch_execz .LBB0_347
.LBB0_363:
	s_waitcnt lgkmcnt(1)
	v_pk_mul_f32 v[12:13], v[224:225], v[12:13]
	s_nop 0
	v_add_f32_e32 v12, v23, v12
	v_pk_mul_f32 v[16:17], v[226:227], v[16:17]
	v_add_f32_e32 v12, v12, v13
	v_add_f32_e32 v12, v12, v16
	s_waitcnt lgkmcnt(0)
	v_pk_mul_f32 v[8:9], v[228:229], v[8:9]
	v_add_f32_e32 v12, v12, v17
	v_add_f32_e32 v8, v12, v8
	v_add_f32_e32 v8, v8, v9
	v_pk_mul_f32 v[4:5], v[230:231], v[4:5]
	s_nop 0
	v_add_f32_e32 v4, v8, v4
	v_add_f32_e32 v23, v4, v5
	s_branch .LBB0_347
.Lgk_in_1:
	ds_read_b128 v[224:227], v31 offset:512
	ds_read_b128 v[228:231], v31 offset:528
	s_branch .LBB0_357
.Lgk_in_2:
	ds_read_b128 v[36:39], v31 offset:1024
	ds_read_b128 v[40:43], v31 offset:1040
	s_branch .LBB0_358
.Lgk_in_3:
	ds_read_b128 v[224:227], v31 offset:1536
	ds_read_b128 v[228:231], v31 offset:1552
	s_branch .LBB0_359
.Lgk_in_4:
	ds_read_b128 v[36:39], v31 offset:2048
	ds_read_b128 v[40:43], v31 offset:2064
	s_branch .LBB0_360
.Lgk_in_5:
	ds_read_b128 v[224:227], v31 offset:2560
	ds_read_b128 v[228:231], v31 offset:2576
	s_branch .LBB0_361
.Lgk_in_6:
	ds_read_b128 v[36:39], v31 offset:3072
	ds_read_b128 v[40:43], v31 offset:3088
	s_branch .LBB0_362
.Lgk_in_7:
	ds_read_b128 v[224:227], v31 offset:3584
	ds_read_b128 v[228:231], v31 offset:3600
	s_branch .LBB0_363

.LBB0_471:
	s_or_b64 exec, exec, s[2:3]
	v_mov_b32_e32 v199, v201
	s_waitcnt lgkmcnt(0)
	s_barrier
	ds_read_b32 v8, v198
	s_movk_i32 s2, 0x200
	s_waitcnt lgkmcnt(0)
	v_cmp_gt_i32_e32 vcc, s2, v8
	s_mov_b64 s[2:3], -1
	s_and_saveexec_b64 s[40:41], vcc
	s_cbranch_execz .LBB0_466
	v_mov_b32_e32 v3, v197
	v_and_b32_e32 v7, 0x7f, v8
	v_ashrrev_i32_e32 v17, 7, v8
	v_ashrrev_i32_e32 v16, 6, v3
	v_lshlrev_b32_e32 v15, 5, v7
	v_lshl_or_b32 v9, v17, 12, v15
	v_lshlrev_b32_e32 v4, 5, v16
	v_bfe_u32 v47, v3, 5, 1
	s_movk_i32 s2, 0x1200
	v_ashrrev_i32_e32 v5, 31, v4
	v_or_b32_e32 v19, v47, v9
	v_mov_b64_e32 v[12:13], s[4:5]
	v_mul_lo_u32 v0, v16, s2
	v_and_b32_e32 v48, 31, v3
	v_mad_i64_i32 v[20:21], s[2:3], v19, s93, v[12:13]
	v_lshlrev_b64 v[52:53], 1, v[4:5]
	v_and_b32_e32 v1, 63, v3
	v_lshl_add_u64 v[20:21], v[20:21], 0, v[52:53]
	v_lshlrev_b32_e32 v54, 1, v48
	v_mov_b32_e32 v55, v2
	v_lshl_add_u64 v[20:21], v[20:21], 0, v[54:55]
	v_or_b32_e32 v58, 64, v1
	v_add_co_u32_e32 v20, vcc, s94, v20
	v_lshrrev_b32_e32 v45, 5, v58
	s_nop 0
	v_addc_co_u32_e32 v21, vcc, 0, v21, vcc
	v_or_b32_e32 v5, v45, v9
	global_load_ushort v50, v[20:21], off offset:1280
	v_mad_i64_i32 v[20:21], s[2:3], v5, s93, v[12:13]
	v_lshl_add_u64 v[20:21], v[20:21], 0, v[52:53]
	v_lshl_add_u64 v[20:21], v[20:21], 0, v[54:55]
	v_or_b32_e32 v60, 0x80, v1
	v_add_co_u32_e32 v20, vcc, s94, v20
	v_lshrrev_b32_e32 v43, 5, v60
	s_nop 0
	v_addc_co_u32_e32 v21, vcc, 0, v21, vcc
	v_or_b32_e32 v5, v43, v9
	global_load_ushort v49, v[20:21], off offset:1280
	v_mad_i64_i32 v[20:21], s[2:3], v5, s93, v[12:13]
	v_lshl_add_u64 v[20:21], v[20:21], 0, v[52:53]
	v_lshl_add_u64 v[20:21], v[20:21], 0, v[54:55]
	v_or_b32_e32 v66, 0xc0, v1
	v_add_co_u32_e32 v20, vcc, s94, v20
	v_lshrrev_b32_e32 v41, 5, v66
	s_nop 0
	v_addc_co_u32_e32 v21, vcc, 0, v21, vcc
	v_or_b32_e32 v5, v41, v9
	global_load_ushort v46, v[20:21], off offset:1280
	v_mad_i64_i32 v[20:21], s[2:3], v5, s93, v[12:13]
	v_lshl_add_u64 v[20:21], v[20:21], 0, v[52:53]
	v_lshl_add_u64 v[20:21], v[20:21], 0, v[54:55]
	v_add_co_u32_e32 v20, vcc, s94, v20
	v_or_b32_e32 v39, 8, v47
	s_nop 0
	v_addc_co_u32_e32 v21, vcc, 0, v21, vcc
	v_or_b32_e32 v5, v39, v9
	global_load_ushort v44, v[20:21], off offset:1280
	v_mad_i64_i32 v[20:21], s[2:3], v5, s93, v[12:13]
	v_lshl_add_u64 v[20:21], v[20:21], 0, v[52:53]
	v_lshl_add_u64 v[20:21], v[20:21], 0, v[54:55]
	v_add_co_u32_e32 v20, vcc, s94, v20
	v_or_b32_e32 v37, 10, v47
	s_nop 0
	v_addc_co_u32_e32 v21, vcc, 0, v21, vcc
	v_or_b32_e32 v5, v37, v9
	global_load_ushort v42, v[20:21], off offset:1280
	v_mad_i64_i32 v[20:21], s[2:3], v5, s93, v[12:13]
	v_lshl_add_u64 v[20:21], v[20:21], 0, v[52:53]
	v_lshl_add_u64 v[20:21], v[20:21], 0, v[54:55]
	v_add_co_u32_e32 v20, vcc, s94, v20
	v_or_b32_e32 v36, 12, v47
	s_nop 0
	v_addc_co_u32_e32 v21, vcc, 0, v21, vcc
	v_or_b32_e32 v5, v36, v9
	global_load_ushort v40, v[20:21], off offset:1280
	v_mad_i64_i32 v[20:21], s[2:3], v5, s93, v[12:13]
	v_lshl_add_u64 v[20:21], v[20:21], 0, v[52:53]
	v_lshl_add_u64 v[20:21], v[20:21], 0, v[54:55]
	v_add_co_u32_e32 v20, vcc, s94, v20
	v_or_b32_e32 v32, 14, v47
	s_nop 0
	v_addc_co_u32_e32 v21, vcc, 0, v21, vcc
	v_or_b32_e32 v5, v32, v9
	global_load_ushort v38, v[20:21], off offset:1280
	v_mad_i64_i32 v[20:21], s[2:3], v5, s93, v[12:13]
	v_lshl_add_u64 v[20:21], v[20:21], 0, v[52:53]
	v_lshl_add_u64 v[20:21], v[20:21], 0, v[54:55]
	v_add_co_u32_e32 v20, vcc, s94, v20
	v_or_b32_e32 v31, 16, v47
	s_nop 0
	v_addc_co_u32_e32 v21, vcc, 0, v21, vcc
	v_or_b32_e32 v5, v31, v9
	global_load_ushort v35, v[20:21], off offset:1280
	v_mad_i64_i32 v[20:21], s[2:3], v5, s93, v[12:13]
	v_lshl_add_u64 v[20:21], v[20:21], 0, v[52:53]
	v_lshl_add_u64 v[20:21], v[20:21], 0, v[54:55]
	v_add_co_u32_e32 v20, vcc, s94, v20
	v_or_b32_e32 v29, 18, v47
	s_nop 0
	v_addc_co_u32_e32 v21, vcc, 0, v21, vcc
	v_or_b32_e32 v5, v29, v9
	global_load_ushort v34, v[20:21], off offset:1280
	v_mad_i64_i32 v[20:21], s[2:3], v5, s93, v[12:13]
	v_lshl_add_u64 v[20:21], v[20:21], 0, v[52:53]
	v_lshl_add_u64 v[20:21], v[20:21], 0, v[54:55]
	v_add_co_u32_e32 v20, vcc, s94, v20
	v_or_b32_e32 v27, 20, v47
	s_nop 0
	v_addc_co_u32_e32 v21, vcc, 0, v21, vcc
	v_or_b32_e32 v5, v27, v9
	global_load_ushort v33, v[20:21], off offset:1280
	v_mad_i64_i32 v[20:21], s[2:3], v5, s93, v[12:13]
	v_lshl_add_u64 v[20:21], v[20:21], 0, v[52:53]
	v_lshl_add_u64 v[20:21], v[20:21], 0, v[54:55]
	v_add_co_u32_e32 v20, vcc, s94, v20
	v_or_b32_e32 v25, 22, v47
	s_nop 0
	v_addc_co_u32_e32 v21, vcc, 0, v21, vcc
	v_or_b32_e32 v5, v25, v9
	global_load_ushort v30, v[20:21], off offset:1280
	v_mad_i64_i32 v[20:21], s[2:3], v5, s93, v[12:13]
	v_lshl_add_u64 v[20:21], v[20:21], 0, v[52:53]
	v_lshl_add_u64 v[20:21], v[20:21], 0, v[54:55]
	v_add_co_u32_e32 v20, vcc, s94, v20
	v_or_b32_e32 v23, 24, v47
	s_nop 0
	v_addc_co_u32_e32 v21, vcc, 0, v21, vcc
	v_or_b32_e32 v5, v23, v9
	global_load_ushort v28, v[20:21], off offset:1280
	v_mad_i64_i32 v[20:21], s[2:3], v5, s93, v[12:13]
	v_lshl_add_u64 v[20:21], v[20:21], 0, v[52:53]
	v_lshl_add_u64 v[20:21], v[20:21], 0, v[54:55]
	v_add_co_u32_e32 v20, vcc, s94, v20
	v_bfe_u32 v70, v3, 3, 3
	s_nop 0
	v_addc_co_u32_e32 v21, vcc, 0, v21, vcc
	global_load_ushort v26, v[20:21], off offset:1280
	v_or_b32_e32 v21, 26, v47
	v_or_b32_e32 v5, v21, v9
	v_mad_i64_i32 v[56:57], s[2:3], v5, s93, v[12:13]
	v_lshl_add_u64 v[56:57], v[56:57], 0, v[52:53]
	v_lshl_add_u64 v[56:57], v[56:57], 0, v[54:55]
	v_add_co_u32_e32 v56, vcc, s94, v56
	v_or_b32_e32 v20, 28, v47
	s_nop 0
	v_addc_co_u32_e32 v57, vcc, 0, v57, vcc
	v_or_b32_e32 v5, v20, v9
	global_load_ushort v24, v[56:57], off offset:1280
	v_mad_i64_i32 v[56:57], s[2:3], v5, s93, v[12:13]
	v_lshl_add_u64 v[56:57], v[56:57], 0, v[52:53]
	v_lshl_add_u64 v[56:57], v[56:57], 0, v[54:55]
	v_add_co_u32_e32 v56, vcc, s94, v56
	v_or_b32_e32 v5, 30, v47
	s_nop 0
	v_addc_co_u32_e32 v57, vcc, 0, v57, vcc
	v_or_b32_e32 v19, v5, v9
	global_load_ushort v22, v[56:57], off offset:1280
	v_mad_i64_i32 v[56:57], s[2:3], v19, s93, v[12:13]
	v_lshl_add_u64 v[52:53], v[56:57], 0, v[52:53]
	v_lshl_add_u64 v[52:53], v[52:53], 0, v[54:55]
	v_add_co_u32_e32 v52, vcc, s94, v52
	v_or_b32_e32 v51, v70, v9
	s_nop 0
	v_addc_co_u32_e32 v53, vcc, 0, v53, vcc
	global_load_ushort v19, v[52:53], off offset:1280
	v_and_b32_e32 v52, 0xffffffc0, v3
	v_ashrrev_i32_e32 v53, 31, v52
	v_mad_i64_i32 v[54:55], s[2:3], v51, s93, v[12:13]
	v_lshlrev_b64 v[64:65], 1, v[52:53]
	v_lshlrev_b32_e32 v51, 4, v3
	v_lshrrev_b32_e32 v71, 3, v58
	v_lshl_add_u64 v[52:53], v[54:55], 0, v[64:65]
	v_and_b32_e32 v68, 0x70, v51
	v_mov_b32_e32 v69, v2
	v_or_b32_e32 v56, v71, v9
	v_lshl_add_u64 v[52:53], v[52:53], 0, v[68:69]
	v_mad_i64_i32 v[56:57], s[2:3], v56, s93, v[12:13]
	v_lshrrev_b32_e32 v72, 3, v60
	v_add_co_u32_e32 v52, vcc, s94, v52
	v_lshl_add_u64 v[56:57], v[56:57], 0, v[64:65]
	v_or_b32_e32 v60, v72, v9
	v_addc_co_u32_e32 v53, vcc, 0, v53, vcc
	v_lshl_add_u64 v[56:57], v[56:57], 0, v[68:69]
	v_mad_i64_i32 v[60:61], s[2:3], v60, s93, v[12:13]
	v_lshrrev_b32_e32 v73, 3, v66
	v_add_co_u32_e32 v56, vcc, s94, v56
	v_lshl_add_u64 v[60:61], v[60:61], 0, v[64:65]
	v_or_b32_e32 v66, v73, v9
	v_addc_co_u32_e32 v57, vcc, 0, v57, vcc
	v_lshl_add_u64 v[60:61], v[60:61], 0, v[68:69]
	v_mad_i64_i32 v[66:67], s[2:3], v66, s93, v[12:13]
	v_add_co_u32_e32 v60, vcc, s94, v60
	v_lshl_add_u64 v[64:65], v[66:67], 0, v[64:65]
	global_load_dwordx4 v[52:55], v[52:53], off offset:1536
	v_addc_co_u32_e32 v61, vcc, 0, v61, vcc
	v_lshl_add_u64 v[64:65], v[64:65], 0, v[68:69]
	global_load_dwordx4 v[56:59], v[56:57], off offset:1536
	v_add_co_u32_e32 v64, vcc, s94, v64
	global_load_dwordx4 v[60:63], v[60:61], off offset:1536
	s_nop 0
	v_addc_co_u32_e32 v65, vcc, 0, v65, vcc
	global_load_dwordx4 v[64:67], v[64:65], off offset:1536
	v_or_b32_e32 v68, v0, v68
	v_mad_u32_u24 v69, v70, s0, v68
	v_readlane_b32 s98, v250, 34
	v_readlane_b32 s99, v250, 35
	v_readlane_b32 s100, v250, 36
	v_readlane_b32 s101, v250, 37
	v_and_b32_e32 v236, 0x7f, v197
	v_or_b32_e32 v238, s14, v236
	v_mov_b32_e32 v239, v2
	v_lshl_add_u64 v[238:239], v[238:239], 2, s[98:99]
	v_add_co_u32_e32 v240, vcc, s94, v238
	global_load_dword v216, v[238:239], off
	global_load_dword v217, v[238:239], off offset:512
	global_load_dword v218, v[238:239], off offset:1024
	global_load_dword v219, v[238:239], off offset:1536
	global_load_dword v220, v[238:239], off offset:2048
	global_load_dword v221, v[238:239], off offset:2560
	global_load_dword v222, v[238:239], off offset:3072
	global_load_dword v223, v[238:239], off offset:3584
	v_addc_co_u32_e32 v241, vcc, 0, v239, vcc
	global_load_dword v224, v[240:241], off
	global_load_dword v225, v[240:241], off offset:512
	global_load_dword v226, v[240:241], off offset:1024
	global_load_dword v227, v[240:241], off offset:1536
	global_load_dword v228, v[240:241], off offset:2048
	global_load_dword v229, v[240:241], off offset:2560
	global_load_dword v230, v[240:241], off offset:3072
	global_load_dword v231, v[240:241], off offset:3584
	v_or_b32_e32 v238, s15, v236
	v_mov_b32_e32 v239, v2
	v_lshl_add_u64 v[238:239], v[238:239], 2, s[100:101]
	global_load_dword v232, v[238:239], off
	v_ashrrev_i32_e32 v238, 4, v197
	v_add_u32_e32 v242, 0x100, v197
	v_add_u32_e32 v238, v238, v9
	v_and_b32_e32 v240, 15, v197
	v_mad_i64_i32 v[238:239], s[2:3], v238, s93, v[12:13]
	v_lshlrev_b32_e32 v240, 1, v240
	v_mov_b32_e32 v241, v2
	v_ashrrev_i32_e32 v242, 4, v242
	v_lshl_add_u64 v[238:239], v[238:239], 0, v[240:241]
	v_add_u32_e32 v242, v242, v9
	v_mad_i64_i32 v[242:243], s[2:3], v242, s93, v[12:13]
	v_add_co_u32_e32 v238, vcc, s94, v238
	v_lshl_add_u64 v[242:243], v[242:243], 0, v[240:241]
	s_nop 0
	v_addc_co_u32_e32 v239, vcc, 0, v239, vcc
	v_add_co_u32_e32 v242, vcc, s94, v242
	global_load_ushort v233, v[238:239], off offset:2560
	s_nop 0
	v_addc_co_u32_e32 v243, vcc, 0, v243, vcc
	global_load_ushort v234, v[242:243], off offset:2560
	s_barrier
	v_readlane_b32 s44, v250, 24
	v_readlane_b32 s45, v250, 25
	v_readlane_b32 s46, v250, 26
	v_readlane_b32 s47, v250, 27
	v_readlane_b32 s48, v250, 28
	v_readlane_b32 s49, v250, 29
	v_readlane_b32 s50, v250, 30
	v_readlane_b32 s51, v250, 31
	v_readlane_b32 s52, v250, 32
	v_readlane_b32 s53, v250, 33
	v_readlane_b32 s54, v250, 34
	v_readlane_b32 s55, v250, 35
	v_readlane_b32 s56, v250, 36
	v_readlane_b32 s57, v250, 37
	v_readlane_b32 s58, v250, 38
	v_readlane_b32 s59, v250, 39
	s_mov_b64 s[44:45], s[52:53]
	s_mov_b64 s[46:47], s[54:55]
	s_mov_b64 s[48:49], s[56:57]
	s_mov_b64 s[50:51], s[58:59]
	s_waitcnt vmcnt(22)
	ds_write_b128 v69, v[52:55] offset:26624
	v_mad_u32_u24 v52, v71, s0, v68
	v_mov_b32_e32 v55, v2
	s_waitcnt vmcnt(21)
	ds_write_b128 v52, v[56:59] offset:26624
	v_mad_u32_u24 v52, v72, s0, v68
	s_waitcnt vmcnt(20)
	ds_write_b128 v52, v[60:63] offset:26624
	v_mad_u32_u24 v52, v73, s0, v68
	v_mov_b32_e32 v73, v2
	s_waitcnt vmcnt(19)
	ds_write_b128 v52, v[64:67] offset:26624
	v_mov_b32_e32 v52, v197
	s_nop 0
	v_and_b32_e32 v74, 0x7f, v52
	v_or_b32_e32 v54, s14, v74
	v_lshl_add_u64 v[54:55], v[54:55], 2, s[46:47]
	v_add_co_u32_e32 v70, vcc, s94, v54
	s_waitcnt vmcnt(0)
	v_mov_b32_e32 v66, v216
	v_mov_b32_e32 v68, v217
	v_mov_b32_e32 v64, v218
	v_mov_b32_e32 v67, v219
	v_mov_b32_e32 v60, v220
	v_mov_b32_e32 v65, v221
	v_mov_b32_e32 v59, v222
	v_mov_b32_e32 v63, v223
	v_addc_co_u32_e32 v71, vcc, 0, v55, vcc
	v_mov_b32_e32 v58, v224
	v_mov_b32_e32 v62, v225
	v_mov_b32_e32 v56, v226
	v_mov_b32_e32 v61, v227
	v_mov_b32_e32 v54, v228
	v_mov_b32_e32 v57, v229
	v_mov_b32_e32 v53, v230
	v_mov_b32_e32 v55, v231
	v_or_b32_e32 v70, s15, v74
	v_mov_b32_e32 v71, v2
	v_lshl_add_u64 v[70:71], v[70:71], 2, s[48:49]
	v_mov_b32_e32 v69, v232
	v_ashrrev_i32_e32 v70, 4, v52
	v_add_u32_e32 v75, 0x100, v52
	v_add_u32_e32 v70, v70, v9
	v_and_b32_e32 v72, 15, v52
	v_mad_i64_i32 v[70:71], s[2:3], v70, s93, v[12:13]
	v_lshlrev_b32_e32 v72, 1, v72
	v_ashrrev_i32_e32 v75, 4, v75
	v_lshl_add_u64 v[70:71], v[70:71], 0, v[72:73]
	v_add_u32_e32 v9, v75, v9
	v_mad_i64_i32 v[12:13], s[2:3], v9, s93, v[12:13]
	v_add_co_u32_e32 v70, vcc, s94, v70
	v_lshl_add_u64 v[12:13], v[12:13], 0, v[72:73]
	s_nop 0
	v_addc_co_u32_e32 v71, vcc, 0, v71, vcc
	v_add_co_u32_e32 v12, vcc, s94, v12
	v_mov_b32_e32 v9, v233
	s_nop 0
	v_addc_co_u32_e32 v13, vcc, 0, v13, vcc
	v_mov_b32_e32 v12, v234
	v_ashrrev_i32_e32 v13, 3, v52
	s_mov_b32 s2, 0xbfb8aa3b
	s_waitcnt vmcnt(1)
	v_lshlrev_b32_e32 v70, 16, v9
	v_lshlrev_b32_e32 v9, 2, v52
	s_waitcnt vmcnt(0)
	v_lshlrev_b32_e32 v12, 16, v12
	ds_write2st64_b32 v9, v70, v12 offset0:64 offset1:68
	v_and_b32_e32 v70, -16, v13
	v_lshlrev_b32_e32 v71, 6, v70
	s_waitcnt lgkmcnt(0)
	s_barrier
	v_lshlrev_b32_e32 v12, 2, v74
	ds_read_b128 v[72:75], v71 offset:16384
	ds_read_b128 v[76:79], v71 offset:16400
	ds_read_b128 v[80:83], v71 offset:16416
	ds_read_b128 v[84:87], v71 offset:16432
	v_or_b32_e32 v13, 15, v13
	s_waitcnt lgkmcnt(3)
	v_mul_f32_e32 v71, v68, v73
	v_fmac_f32_e32 v71, v66, v72
	v_mul_f32_e32 v72, v67, v75
	v_fmac_f32_e32 v72, v64, v74
	v_add_f32_e32 v71, v71, v72
	s_waitcnt lgkmcnt(2)
	v_mul_f32_e32 v72, v65, v77
	v_mul_f32_e32 v73, v63, v79
	v_fmac_f32_e32 v72, v60, v76
	v_fmac_f32_e32 v73, v59, v78
	v_add_f32_e32 v71, v69, v71
	v_add_f32_e32 v72, v72, v73
	v_add_f32_e32 v71, v71, v72
	s_waitcnt lgkmcnt(1)
	v_mul_f32_e32 v72, v62, v81
	v_mul_f32_e32 v73, v61, v83
	v_fmac_f32_e32 v72, v58, v80
	v_fmac_f32_e32 v73, v56, v82
	v_add_f32_e32 v72, v72, v73
	v_add_f32_e32 v71, v71, v72
	s_waitcnt lgkmcnt(0)
	v_mul_f32_e32 v72, v57, v85
	v_mul_f32_e32 v73, v55, v87
	v_fmac_f32_e32 v72, v54, v84
	v_fmac_f32_e32 v73, v53, v86
	v_add_f32_e32 v72, v72, v73
	v_add_f32_e32 v71, v71, v72
	v_min_f32_e32 v72, 0, v71
	v_mul_f32_e64 v71, |v71|, s2
	v_exp_f32_e32 v71, v71
	s_nop 0
	v_add_f32_e32 v71, 1.0, v71
	v_cmp_gt_f32_e32 vcc, s22, v71
	s_nop 1
	v_cndmask_b32_e64 v73, 0, 32, vcc
	v_ldexp_f32 v71, v71, v73
	v_log_f32_e32 v71, v71
	s_nop 0
	v_mul_f32_e32 v73, 0x3f317217, v71
	v_fma_f32 v73, v71, s37, -v73
	v_fmac_f32_e32 v73, 0x3377d1cf, v71
	v_fmac_f32_e32 v73, 0x3f317217, v71
	v_cmp_lt_f32_e64 s[38:39], |v71|, s1
	s_nop 1
	v_cndmask_b32_e64 v71, v71, v73, s[38:39]
	v_cndmask_b32_e32 v73, 0, v213, vcc
	v_sub_f32_e32 v71, v71, v73
	v_sub_f32_e32 v71, v72, v71
	v_mul_f32_e32 v71, 0x3d800000, v71
	v_lshl_or_b32 v72, v70, 9, v12
	ds_write_b32 v72, v71
	v_or_b32_e32 v71, 1, v70
	v_lshlrev_b32_e32 v84, 6, v71
	ds_read_b128 v[72:75], v84 offset:16384
	ds_read_b128 v[76:79], v84 offset:16400
	ds_read_b128 v[80:83], v84 offset:16416
	ds_read_b128 v[84:87], v84 offset:16432
	v_lshl_or_b32 v71, v71, 9, v12
	s_waitcnt lgkmcnt(3)
	v_mul_f32_e32 v73, v68, v73
	v_fmac_f32_e32 v73, v66, v72
	v_mul_f32_e32 v72, v67, v75
	v_fmac_f32_e32 v72, v64, v74
	v_add_f32_e32 v72, v73, v72
	s_waitcnt lgkmcnt(2)
	v_mul_f32_e32 v73, v65, v77
	v_mul_f32_e32 v74, v63, v79
	v_fmac_f32_e32 v73, v60, v76
	v_fmac_f32_e32 v74, v59, v78
	v_add_f32_e32 v72, v69, v72
	v_add_f32_e32 v73, v73, v74
	v_add_f32_e32 v72, v72, v73
	s_waitcnt lgkmcnt(1)
	v_mul_f32_e32 v73, v62, v81
	v_mul_f32_e32 v74, v61, v83
	v_fmac_f32_e32 v73, v58, v80
	v_fmac_f32_e32 v74, v56, v82
	v_add_f32_e32 v73, v73, v74
	v_add_f32_e32 v72, v72, v73
	s_waitcnt lgkmcnt(0)
	v_mul_f32_e32 v73, v57, v85
	v_mul_f32_e32 v74, v55, v87
	v_fmac_f32_e32 v73, v54, v84
	v_fmac_f32_e32 v74, v53, v86
	v_add_f32_e32 v73, v73, v74
	v_add_f32_e32 v72, v72, v73
	v_min_f32_e32 v73, 0, v72
	v_mul_f32_e64 v72, |v72|, s2
	v_exp_f32_e32 v72, v72
	s_nop 0
	v_add_f32_e32 v72, 1.0, v72
	v_cmp_gt_f32_e32 vcc, s22, v72
	s_nop 1
	v_cndmask_b32_e64 v74, 0, 32, vcc
	v_ldexp_f32 v72, v72, v74
	v_log_f32_e32 v72, v72
	s_nop 0
	v_mul_f32_e32 v74, 0x3f317217, v72
	v_fma_f32 v74, v72, s37, -v74
	v_fmac_f32_e32 v74, 0x3377d1cf, v72
	v_fmac_f32_e32 v74, 0x3f317217, v72
	v_cmp_lt_f32_e64 s[38:39], |v72|, s1
	s_nop 1
	v_cndmask_b32_e64 v72, v72, v74, s[38:39]
	v_cndmask_b32_e32 v74, 0, v213, vcc
	v_sub_f32_e32 v72, v72, v74
	v_sub_f32_e32 v72, v73, v72
	v_mul_f32_e32 v72, 0x3d800000, v72
	ds_write_b32 v71, v72
	v_or_b32_e32 v71, 2, v70
	v_lshlrev_b32_e32 v84, 6, v71
	ds_read_b128 v[72:75], v84 offset:16384
	ds_read_b128 v[76:79], v84 offset:16400
	ds_read_b128 v[80:83], v84 offset:16416
	ds_read_b128 v[84:87], v84 offset:16432
	v_lshl_or_b32 v71, v71, 9, v12
	s_waitcnt lgkmcnt(3)
	v_mul_f32_e32 v73, v68, v73
	v_fmac_f32_e32 v73, v66, v72
	v_mul_f32_e32 v72, v67, v75
	v_fmac_f32_e32 v72, v64, v74
	v_add_f32_e32 v72, v73, v72
	s_waitcnt lgkmcnt(2)
	v_mul_f32_e32 v73, v65, v77
	v_mul_f32_e32 v74, v63, v79
	v_fmac_f32_e32 v73, v60, v76
	v_fmac_f32_e32 v74, v59, v78
	v_add_f32_e32 v72, v69, v72
	v_add_f32_e32 v73, v73, v74
	v_add_f32_e32 v72, v72, v73
	s_waitcnt lgkmcnt(1)
	v_mul_f32_e32 v73, v62, v81
	v_mul_f32_e32 v74, v61, v83
	v_fmac_f32_e32 v73, v58, v80
	v_fmac_f32_e32 v74, v56, v82
	v_add_f32_e32 v73, v73, v74
	v_add_f32_e32 v72, v72, v73
	s_waitcnt lgkmcnt(0)
	v_mul_f32_e32 v73, v57, v85
	v_mul_f32_e32 v74, v55, v87
	v_fmac_f32_e32 v73, v54, v84
	v_fmac_f32_e32 v74, v53, v86
	v_add_f32_e32 v73, v73, v74
	v_add_f32_e32 v72, v72, v73
	v_min_f32_e32 v73, 0, v72
	v_mul_f32_e64 v72, |v72|, s2
	v_exp_f32_e32 v72, v72
	s_nop 0
	v_add_f32_e32 v72, 1.0, v72
	v_cmp_gt_f32_e32 vcc, s22, v72
	s_nop 1
	v_cndmask_b32_e64 v74, 0, 32, vcc
	v_ldexp_f32 v72, v72, v74
	v_log_f32_e32 v72, v72
	s_nop 0
	v_mul_f32_e32 v74, 0x3f317217, v72
	v_fma_f32 v74, v72, s37, -v74
	v_fmac_f32_e32 v74, 0x3377d1cf, v72
	v_fmac_f32_e32 v74, 0x3f317217, v72
	v_cmp_lt_f32_e64 s[38:39], |v72|, s1
	s_nop 1
	v_cndmask_b32_e64 v72, v72, v74, s[38:39]
	v_cndmask_b32_e32 v74, 0, v213, vcc
	v_sub_f32_e32 v72, v72, v74
	v_sub_f32_e32 v72, v73, v72
	v_mul_f32_e32 v72, 0x3d800000, v72
	ds_write_b32 v71, v72
	v_or_b32_e32 v71, 3, v70
	v_lshlrev_b32_e32 v84, 6, v71
	ds_read_b128 v[72:75], v84 offset:16384
	ds_read_b128 v[76:79], v84 offset:16400
	ds_read_b128 v[80:83], v84 offset:16416
	ds_read_b128 v[84:87], v84 offset:16432
	v_lshl_or_b32 v71, v71, 9, v12
	s_waitcnt lgkmcnt(3)
	v_mul_f32_e32 v73, v68, v73
	v_fmac_f32_e32 v73, v66, v72
	v_mul_f32_e32 v72, v67, v75
	v_fmac_f32_e32 v72, v64, v74
	v_add_f32_e32 v72, v73, v72
	s_waitcnt lgkmcnt(2)
	v_mul_f32_e32 v73, v65, v77
	v_mul_f32_e32 v74, v63, v79
	v_fmac_f32_e32 v73, v60, v76
	v_fmac_f32_e32 v74, v59, v78
	v_add_f32_e32 v72, v69, v72
	v_add_f32_e32 v73, v73, v74
	v_add_f32_e32 v72, v72, v73
	s_waitcnt lgkmcnt(1)
	v_mul_f32_e32 v73, v62, v81
	v_mul_f32_e32 v74, v61, v83
	v_fmac_f32_e32 v73, v58, v80
	v_fmac_f32_e32 v74, v56, v82
	v_add_f32_e32 v73, v73, v74
	v_add_f32_e32 v72, v72, v73
	s_waitcnt lgkmcnt(0)
	v_mul_f32_e32 v73, v57, v85
	v_mul_f32_e32 v74, v55, v87
	v_fmac_f32_e32 v73, v54, v84
	v_fmac_f32_e32 v74, v53, v86
	v_add_f32_e32 v73, v73, v74
	v_add_f32_e32 v72, v72, v73
	v_min_f32_e32 v73, 0, v72
	v_mul_f32_e64 v72, |v72|, s2
	v_exp_f32_e32 v72, v72
	s_nop 0
	v_add_f32_e32 v72, 1.0, v72
	v_cmp_gt_f32_e32 vcc, s22, v72
	s_nop 1
	v_cndmask_b32_e64 v74, 0, 32, vcc
	v_ldexp_f32 v72, v72, v74
	v_log_f32_e32 v72, v72
	s_nop 0
	v_mul_f32_e32 v74, 0x3f317217, v72
	v_fma_f32 v74, v72, s37, -v74
	v_fmac_f32_e32 v74, 0x3377d1cf, v72
	v_fmac_f32_e32 v74, 0x3f317217, v72
	v_cmp_lt_f32_e64 s[38:39], |v72|, s1
	s_nop 1
	v_cndmask_b32_e64 v72, v72, v74, s[38:39]
	v_cndmask_b32_e32 v74, 0, v213, vcc
	v_sub_f32_e32 v72, v72, v74
	v_sub_f32_e32 v72, v73, v72
	v_mul_f32_e32 v72, 0x3d800000, v72
	ds_write_b32 v71, v72
	v_or_b32_e32 v71, 4, v70
	v_lshlrev_b32_e32 v84, 6, v71
	ds_read_b128 v[72:75], v84 offset:16384
	ds_read_b128 v[76:79], v84 offset:16400
	ds_read_b128 v[80:83], v84 offset:16416
	ds_read_b128 v[84:87], v84 offset:16432
	v_lshl_or_b32 v71, v71, 9, v12
	s_waitcnt lgkmcnt(3)
	v_mul_f32_e32 v73, v68, v73
	v_fmac_f32_e32 v73, v66, v72
	v_mul_f32_e32 v72, v67, v75
	v_fmac_f32_e32 v72, v64, v74
	v_add_f32_e32 v72, v73, v72
	s_waitcnt lgkmcnt(2)
	v_mul_f32_e32 v73, v65, v77
	v_mul_f32_e32 v74, v63, v79
	v_fmac_f32_e32 v73, v60, v76
	v_fmac_f32_e32 v74, v59, v78
	v_add_f32_e32 v72, v69, v72
	v_add_f32_e32 v73, v73, v74
	v_add_f32_e32 v72, v72, v73
	s_waitcnt lgkmcnt(1)
	v_mul_f32_e32 v73, v62, v81
	v_mul_f32_e32 v74, v61, v83
	v_fmac_f32_e32 v73, v58, v80
	v_fmac_f32_e32 v74, v56, v82
	v_add_f32_e32 v73, v73, v74
	v_add_f32_e32 v72, v72, v73
	s_waitcnt lgkmcnt(0)
	v_mul_f32_e32 v73, v57, v85
	v_mul_f32_e32 v74, v55, v87
	v_fmac_f32_e32 v73, v54, v84
	v_fmac_f32_e32 v74, v53, v86
	v_add_f32_e32 v73, v73, v74
	v_add_f32_e32 v72, v72, v73
	v_min_f32_e32 v73, 0, v72
	v_mul_f32_e64 v72, |v72|, s2
	v_exp_f32_e32 v72, v72
	s_nop 0
	v_add_f32_e32 v72, 1.0, v72
	v_cmp_gt_f32_e32 vcc, s22, v72
	s_nop 1
	v_cndmask_b32_e64 v74, 0, 32, vcc
	v_ldexp_f32 v72, v72, v74
	v_log_f32_e32 v72, v72
	s_nop 0
	v_mul_f32_e32 v74, 0x3f317217, v72
	v_fma_f32 v74, v72, s37, -v74
	v_fmac_f32_e32 v74, 0x3377d1cf, v72
	v_fmac_f32_e32 v74, 0x3f317217, v72
	v_cmp_lt_f32_e64 s[38:39], |v72|, s1
	s_nop 1
	v_cndmask_b32_e64 v72, v72, v74, s[38:39]
	v_cndmask_b32_e32 v74, 0, v213, vcc
	v_sub_f32_e32 v72, v72, v74
	v_sub_f32_e32 v72, v73, v72
	v_mul_f32_e32 v72, 0x3d800000, v72
	ds_write_b32 v71, v72
	v_or_b32_e32 v71, 5, v70
	v_lshlrev_b32_e32 v84, 6, v71
	ds_read_b128 v[72:75], v84 offset:16384
	ds_read_b128 v[76:79], v84 offset:16400
	ds_read_b128 v[80:83], v84 offset:16416
	ds_read_b128 v[84:87], v84 offset:16432
	v_lshl_or_b32 v71, v71, 9, v12
	s_waitcnt lgkmcnt(3)
	v_mul_f32_e32 v73, v68, v73
	v_fmac_f32_e32 v73, v66, v72
	v_mul_f32_e32 v72, v67, v75
	v_fmac_f32_e32 v72, v64, v74
	v_add_f32_e32 v72, v73, v72
	s_waitcnt lgkmcnt(2)
	v_mul_f32_e32 v73, v65, v77
	v_mul_f32_e32 v74, v63, v79
	v_fmac_f32_e32 v73, v60, v76
	v_fmac_f32_e32 v74, v59, v78
	v_add_f32_e32 v72, v69, v72
	v_add_f32_e32 v73, v73, v74
	v_add_f32_e32 v72, v72, v73
	s_waitcnt lgkmcnt(1)
	v_mul_f32_e32 v73, v62, v81
	v_mul_f32_e32 v74, v61, v83
	v_fmac_f32_e32 v73, v58, v80
	v_fmac_f32_e32 v74, v56, v82
	v_add_f32_e32 v73, v73, v74
	v_add_f32_e32 v72, v72, v73
	s_waitcnt lgkmcnt(0)
	v_mul_f32_e32 v73, v57, v85
	v_mul_f32_e32 v74, v55, v87
	v_fmac_f32_e32 v73, v54, v84
	v_fmac_f32_e32 v74, v53, v86
	v_add_f32_e32 v73, v73, v74
	v_add_f32_e32 v72, v72, v73
	v_min_f32_e32 v73, 0, v72
	v_mul_f32_e64 v72, |v72|, s2
	v_exp_f32_e32 v72, v72
	s_nop 0
	v_add_f32_e32 v72, 1.0, v72
	v_cmp_gt_f32_e32 vcc, s22, v72
	s_nop 1
	v_cndmask_b32_e64 v74, 0, 32, vcc
	v_ldexp_f32 v72, v72, v74
	v_log_f32_e32 v72, v72
	s_nop 0
	v_mul_f32_e32 v74, 0x3f317217, v72
	v_fma_f32 v74, v72, s37, -v74
	v_fmac_f32_e32 v74, 0x3377d1cf, v72
	v_fmac_f32_e32 v74, 0x3f317217, v72
	v_cmp_lt_f32_e64 s[38:39], |v72|, s1
	s_nop 1
	v_cndmask_b32_e64 v72, v72, v74, s[38:39]
	v_cndmask_b32_e32 v74, 0, v213, vcc
	v_sub_f32_e32 v72, v72, v74
	v_sub_f32_e32 v72, v73, v72
	v_mul_f32_e32 v72, 0x3d800000, v72
	ds_write_b32 v71, v72
	v_or_b32_e32 v71, 6, v70
	v_lshlrev_b32_e32 v84, 6, v71
	ds_read_b128 v[72:75], v84 offset:16384
	ds_read_b128 v[76:79], v84 offset:16400
	ds_read_b128 v[80:83], v84 offset:16416
	ds_read_b128 v[84:87], v84 offset:16432
	v_lshl_or_b32 v71, v71, 9, v12
	s_waitcnt lgkmcnt(3)
	v_mul_f32_e32 v73, v68, v73
	v_fmac_f32_e32 v73, v66, v72
	v_mul_f32_e32 v72, v67, v75
	v_fmac_f32_e32 v72, v64, v74
	v_add_f32_e32 v72, v73, v72
	s_waitcnt lgkmcnt(2)
	v_mul_f32_e32 v73, v65, v77
	v_mul_f32_e32 v74, v63, v79
	v_fmac_f32_e32 v73, v60, v76
	v_fmac_f32_e32 v74, v59, v78
	v_add_f32_e32 v72, v69, v72
	v_add_f32_e32 v73, v73, v74
	v_add_f32_e32 v72, v72, v73
	s_waitcnt lgkmcnt(1)
	v_mul_f32_e32 v73, v62, v81
	v_mul_f32_e32 v74, v61, v83
	v_fmac_f32_e32 v73, v58, v80
	v_fmac_f32_e32 v74, v56, v82
	v_add_f32_e32 v73, v73, v74
	v_add_f32_e32 v72, v72, v73
	s_waitcnt lgkmcnt(0)
	v_mul_f32_e32 v73, v57, v85
	v_mul_f32_e32 v74, v55, v87
	v_fmac_f32_e32 v73, v54, v84
	v_fmac_f32_e32 v74, v53, v86
	v_add_f32_e32 v73, v73, v74
	v_add_f32_e32 v72, v72, v73
	v_min_f32_e32 v73, 0, v72
	v_mul_f32_e64 v72, |v72|, s2
	v_exp_f32_e32 v72, v72
	s_nop 0
	v_add_f32_e32 v72, 1.0, v72
	v_cmp_gt_f32_e32 vcc, s22, v72
	s_nop 1
	v_cndmask_b32_e64 v74, 0, 32, vcc
	v_ldexp_f32 v72, v72, v74
	v_log_f32_e32 v72, v72
	s_nop 0
	v_mul_f32_e32 v74, 0x3f317217, v72
	v_fma_f32 v74, v72, s37, -v74
	v_fmac_f32_e32 v74, 0x3377d1cf, v72
	v_fmac_f32_e32 v74, 0x3f317217, v72
	v_cmp_lt_f32_e64 s[38:39], |v72|, s1
	s_nop 1
	v_cndmask_b32_e64 v72, v72, v74, s[38:39]
	v_cndmask_b32_e32 v74, 0, v213, vcc
	v_sub_f32_e32 v72, v72, v74
	v_sub_f32_e32 v72, v73, v72
	v_mul_f32_e32 v72, 0x3d800000, v72
	ds_write_b32 v71, v72
	v_or_b32_e32 v71, 7, v70
	v_lshlrev_b32_e32 v84, 6, v71
	ds_read_b128 v[72:75], v84 offset:16384
	ds_read_b128 v[76:79], v84 offset:16400
	ds_read_b128 v[80:83], v84 offset:16416
	ds_read_b128 v[84:87], v84 offset:16432
	v_lshl_or_b32 v71, v71, 9, v12
	s_waitcnt lgkmcnt(3)
	v_mul_f32_e32 v73, v68, v73
	v_fmac_f32_e32 v73, v66, v72
	v_mul_f32_e32 v72, v67, v75
	v_fmac_f32_e32 v72, v64, v74
	v_add_f32_e32 v72, v73, v72
	s_waitcnt lgkmcnt(2)
	v_mul_f32_e32 v73, v65, v77
	v_mul_f32_e32 v74, v63, v79
	v_fmac_f32_e32 v73, v60, v76
	v_fmac_f32_e32 v74, v59, v78
	v_add_f32_e32 v72, v69, v72
	v_add_f32_e32 v73, v73, v74
	v_add_f32_e32 v72, v72, v73
	s_waitcnt lgkmcnt(1)
	v_mul_f32_e32 v73, v62, v81
	v_mul_f32_e32 v74, v61, v83
	v_fmac_f32_e32 v73, v58, v80
	v_fmac_f32_e32 v74, v56, v82
	v_add_f32_e32 v73, v73, v74
	v_add_f32_e32 v72, v72, v73
	s_waitcnt lgkmcnt(0)
	v_mul_f32_e32 v73, v57, v85
	v_mul_f32_e32 v74, v55, v87
	v_fmac_f32_e32 v73, v54, v84
	v_fmac_f32_e32 v74, v53, v86
	v_add_f32_e32 v73, v73, v74
	v_add_f32_e32 v72, v72, v73
	v_min_f32_e32 v73, 0, v72
	v_mul_f32_e64 v72, |v72|, s2
	v_exp_f32_e32 v72, v72
	s_nop 0
	v_add_f32_e32 v72, 1.0, v72
	v_cmp_gt_f32_e32 vcc, s22, v72
	s_nop 1
	v_cndmask_b32_e64 v74, 0, 32, vcc
	v_ldexp_f32 v72, v72, v74
	v_log_f32_e32 v72, v72
	s_nop 0
	v_mul_f32_e32 v74, 0x3f317217, v72
	v_fma_f32 v74, v72, s37, -v74
	v_fmac_f32_e32 v74, 0x3377d1cf, v72
	v_fmac_f32_e32 v74, 0x3f317217, v72
	v_cmp_lt_f32_e64 s[38:39], |v72|, s1
	s_nop 1
	v_cndmask_b32_e64 v72, v72, v74, s[38:39]
	v_cndmask_b32_e32 v74, 0, v213, vcc
	v_sub_f32_e32 v72, v72, v74
	v_sub_f32_e32 v72, v73, v72
	v_mul_f32_e32 v72, 0x3d800000, v72
	ds_write_b32 v71, v72
	v_or_b32_e32 v71, 8, v70
	v_lshlrev_b32_e32 v84, 6, v71
	ds_read_b128 v[72:75], v84 offset:16384
	ds_read_b128 v[76:79], v84 offset:16400
	ds_read_b128 v[80:83], v84 offset:16416
	ds_read_b128 v[84:87], v84 offset:16432
	v_lshl_or_b32 v71, v71, 9, v12
	s_waitcnt lgkmcnt(3)
	v_mul_f32_e32 v73, v68, v73
	v_fmac_f32_e32 v73, v66, v72
	v_mul_f32_e32 v72, v67, v75
	v_fmac_f32_e32 v72, v64, v74
	v_add_f32_e32 v72, v73, v72
	s_waitcnt lgkmcnt(2)
	v_mul_f32_e32 v73, v65, v77
	v_mul_f32_e32 v74, v63, v79
	v_fmac_f32_e32 v73, v60, v76
	v_fmac_f32_e32 v74, v59, v78
	v_add_f32_e32 v72, v69, v72
	v_add_f32_e32 v73, v73, v74
	v_add_f32_e32 v72, v72, v73
	s_waitcnt lgkmcnt(1)
	v_mul_f32_e32 v73, v62, v81
	v_mul_f32_e32 v74, v61, v83
	v_fmac_f32_e32 v73, v58, v80
	v_fmac_f32_e32 v74, v56, v82
	v_add_f32_e32 v73, v73, v74
	v_add_f32_e32 v72, v72, v73
	s_waitcnt lgkmcnt(0)
	v_mul_f32_e32 v73, v57, v85
	v_mul_f32_e32 v74, v55, v87
	v_fmac_f32_e32 v73, v54, v84
	v_fmac_f32_e32 v74, v53, v86
	v_add_f32_e32 v73, v73, v74
	v_add_f32_e32 v72, v72, v73
	v_min_f32_e32 v73, 0, v72
	v_mul_f32_e64 v72, |v72|, s2
	v_exp_f32_e32 v72, v72
	s_nop 0
	v_add_f32_e32 v72, 1.0, v72
	v_cmp_gt_f32_e32 vcc, s22, v72
	s_nop 1
	v_cndmask_b32_e64 v74, 0, 32, vcc
	v_ldexp_f32 v72, v72, v74
	v_log_f32_e32 v72, v72
	s_nop 0
	v_mul_f32_e32 v74, 0x3f317217, v72
	v_fma_f32 v74, v72, s37, -v74
	v_fmac_f32_e32 v74, 0x3377d1cf, v72
	v_fmac_f32_e32 v74, 0x3f317217, v72
	v_cmp_lt_f32_e64 s[38:39], |v72|, s1
	s_nop 1
	v_cndmask_b32_e64 v72, v72, v74, s[38:39]
	v_cndmask_b32_e32 v74, 0, v213, vcc
	v_sub_f32_e32 v72, v72, v74
	v_sub_f32_e32 v72, v73, v72
	v_mul_f32_e32 v72, 0x3d800000, v72
	ds_write_b32 v71, v72
	v_or_b32_e32 v71, 9, v70
	v_lshlrev_b32_e32 v84, 6, v71
	ds_read_b128 v[72:75], v84 offset:16384
	ds_read_b128 v[76:79], v84 offset:16400
	ds_read_b128 v[80:83], v84 offset:16416
	ds_read_b128 v[84:87], v84 offset:16432
	v_lshl_or_b32 v71, v71, 9, v12
	s_waitcnt lgkmcnt(3)
	v_mul_f32_e32 v73, v68, v73
	v_fmac_f32_e32 v73, v66, v72
	v_mul_f32_e32 v72, v67, v75
	v_fmac_f32_e32 v72, v64, v74
	v_add_f32_e32 v72, v73, v72
	s_waitcnt lgkmcnt(2)
	v_mul_f32_e32 v73, v65, v77
	v_mul_f32_e32 v74, v63, v79
	v_fmac_f32_e32 v73, v60, v76
	v_fmac_f32_e32 v74, v59, v78
	v_add_f32_e32 v72, v69, v72
	v_add_f32_e32 v73, v73, v74
	v_add_f32_e32 v72, v72, v73
	s_waitcnt lgkmcnt(1)
	v_mul_f32_e32 v73, v62, v81
	v_mul_f32_e32 v74, v61, v83
	v_fmac_f32_e32 v73, v58, v80
	v_fmac_f32_e32 v74, v56, v82
	v_add_f32_e32 v73, v73, v74
	v_add_f32_e32 v72, v72, v73
	s_waitcnt lgkmcnt(0)
	v_mul_f32_e32 v73, v57, v85
	v_mul_f32_e32 v74, v55, v87
	v_fmac_f32_e32 v73, v54, v84
	v_fmac_f32_e32 v74, v53, v86
	v_add_f32_e32 v73, v73, v74
	v_add_f32_e32 v72, v72, v73
	v_min_f32_e32 v73, 0, v72
	v_mul_f32_e64 v72, |v72|, s2
	v_exp_f32_e32 v72, v72
	s_nop 0
	v_add_f32_e32 v72, 1.0, v72
	v_cmp_gt_f32_e32 vcc, s22, v72
	s_nop 1
	v_cndmask_b32_e64 v74, 0, 32, vcc
	v_ldexp_f32 v72, v72, v74
	v_log_f32_e32 v72, v72
	s_nop 0
	v_mul_f32_e32 v74, 0x3f317217, v72
	v_fma_f32 v74, v72, s37, -v74
	v_fmac_f32_e32 v74, 0x3377d1cf, v72
	v_fmac_f32_e32 v74, 0x3f317217, v72
	v_cmp_lt_f32_e64 s[38:39], |v72|, s1
	s_nop 1
	v_cndmask_b32_e64 v72, v72, v74, s[38:39]
	v_cndmask_b32_e32 v74, 0, v213, vcc
	v_sub_f32_e32 v72, v72, v74
	v_sub_f32_e32 v72, v73, v72
	v_mul_f32_e32 v72, 0x3d800000, v72
	ds_write_b32 v71, v72
	v_or_b32_e32 v71, 10, v70
	v_lshlrev_b32_e32 v84, 6, v71
	ds_read_b128 v[72:75], v84 offset:16384
	ds_read_b128 v[76:79], v84 offset:16400
	ds_read_b128 v[80:83], v84 offset:16416
	ds_read_b128 v[84:87], v84 offset:16432
	v_lshl_or_b32 v71, v71, 9, v12
	s_waitcnt lgkmcnt(3)
	v_mul_f32_e32 v73, v68, v73
	v_fmac_f32_e32 v73, v66, v72
	v_mul_f32_e32 v72, v67, v75
	v_fmac_f32_e32 v72, v64, v74
	v_add_f32_e32 v72, v73, v72
	s_waitcnt lgkmcnt(2)
	v_mul_f32_e32 v73, v65, v77
	v_mul_f32_e32 v74, v63, v79
	v_fmac_f32_e32 v73, v60, v76
	v_fmac_f32_e32 v74, v59, v78
	v_add_f32_e32 v72, v69, v72
	v_add_f32_e32 v73, v73, v74
	v_add_f32_e32 v72, v72, v73
	s_waitcnt lgkmcnt(1)
	v_mul_f32_e32 v73, v62, v81
	v_mul_f32_e32 v74, v61, v83
	v_fmac_f32_e32 v73, v58, v80
	v_fmac_f32_e32 v74, v56, v82
	v_add_f32_e32 v73, v73, v74
	v_add_f32_e32 v72, v72, v73
	s_waitcnt lgkmcnt(0)
	v_mul_f32_e32 v73, v57, v85
	v_mul_f32_e32 v74, v55, v87
	v_fmac_f32_e32 v73, v54, v84
	v_fmac_f32_e32 v74, v53, v86
	v_add_f32_e32 v73, v73, v74
	v_add_f32_e32 v72, v72, v73
	v_min_f32_e32 v73, 0, v72
	v_mul_f32_e64 v72, |v72|, s2
	v_exp_f32_e32 v72, v72
	s_nop 0
	v_add_f32_e32 v72, 1.0, v72
	v_cmp_gt_f32_e32 vcc, s22, v72
	s_nop 1
	v_cndmask_b32_e64 v74, 0, 32, vcc
	v_ldexp_f32 v72, v72, v74
	v_log_f32_e32 v72, v72
	s_nop 0
	v_mul_f32_e32 v74, 0x3f317217, v72
	v_fma_f32 v74, v72, s37, -v74
	v_fmac_f32_e32 v74, 0x3377d1cf, v72
	v_fmac_f32_e32 v74, 0x3f317217, v72
	v_cmp_lt_f32_e64 s[38:39], |v72|, s1
	s_nop 1
	v_cndmask_b32_e64 v72, v72, v74, s[38:39]
	v_cndmask_b32_e32 v74, 0, v213, vcc
	v_sub_f32_e32 v72, v72, v74
	v_sub_f32_e32 v72, v73, v72
	v_mul_f32_e32 v72, 0x3d800000, v72
	ds_write_b32 v71, v72
	v_or_b32_e32 v71, 11, v70
	v_lshlrev_b32_e32 v84, 6, v71
	ds_read_b128 v[72:75], v84 offset:16384
	ds_read_b128 v[76:79], v84 offset:16400
	ds_read_b128 v[80:83], v84 offset:16416
	ds_read_b128 v[84:87], v84 offset:16432
	v_lshl_or_b32 v71, v71, 9, v12
	s_waitcnt lgkmcnt(3)
	v_mul_f32_e32 v73, v68, v73
	v_fmac_f32_e32 v73, v66, v72
	v_mul_f32_e32 v72, v67, v75
	v_fmac_f32_e32 v72, v64, v74
	v_add_f32_e32 v72, v73, v72
	s_waitcnt lgkmcnt(2)
	v_mul_f32_e32 v73, v65, v77
	v_mul_f32_e32 v74, v63, v79
	v_fmac_f32_e32 v73, v60, v76
	v_fmac_f32_e32 v74, v59, v78
	v_add_f32_e32 v72, v69, v72
	v_add_f32_e32 v73, v73, v74
	v_add_f32_e32 v72, v72, v73
	s_waitcnt lgkmcnt(1)
	v_mul_f32_e32 v73, v62, v81
	v_mul_f32_e32 v74, v61, v83
	v_fmac_f32_e32 v73, v58, v80
	v_fmac_f32_e32 v74, v56, v82
	v_add_f32_e32 v73, v73, v74
	v_add_f32_e32 v72, v72, v73
	s_waitcnt lgkmcnt(0)
	v_mul_f32_e32 v73, v57, v85
	v_mul_f32_e32 v74, v55, v87
	v_fmac_f32_e32 v73, v54, v84
	v_fmac_f32_e32 v74, v53, v86
	v_add_f32_e32 v73, v73, v74
	v_add_f32_e32 v72, v72, v73
	v_min_f32_e32 v73, 0, v72
	v_mul_f32_e64 v72, |v72|, s2
	v_exp_f32_e32 v72, v72
	s_nop 0
	v_add_f32_e32 v72, 1.0, v72
	v_cmp_gt_f32_e32 vcc, s22, v72
	s_nop 1
	v_cndmask_b32_e64 v74, 0, 32, vcc
	v_ldexp_f32 v72, v72, v74
	v_log_f32_e32 v72, v72
	s_nop 0
	v_mul_f32_e32 v74, 0x3f317217, v72
	v_fma_f32 v74, v72, s37, -v74
	v_fmac_f32_e32 v74, 0x3377d1cf, v72
	v_fmac_f32_e32 v74, 0x3f317217, v72
	v_cmp_lt_f32_e64 s[38:39], |v72|, s1
	s_nop 1
	v_cndmask_b32_e64 v72, v72, v74, s[38:39]
	v_cndmask_b32_e32 v74, 0, v213, vcc
	v_sub_f32_e32 v72, v72, v74
	v_sub_f32_e32 v72, v73, v72
	v_mul_f32_e32 v72, 0x3d800000, v72
	ds_write_b32 v71, v72
	v_or_b32_e32 v71, 12, v70
	v_lshlrev_b32_e32 v84, 6, v71
	ds_read_b128 v[72:75], v84 offset:16384
	ds_read_b128 v[76:79], v84 offset:16400
	ds_read_b128 v[80:83], v84 offset:16416
	ds_read_b128 v[84:87], v84 offset:16432
	v_lshl_or_b32 v71, v71, 9, v12
	s_waitcnt lgkmcnt(3)
	v_mul_f32_e32 v73, v68, v73
	v_fmac_f32_e32 v73, v66, v72
	v_mul_f32_e32 v72, v67, v75
	v_fmac_f32_e32 v72, v64, v74
	v_add_f32_e32 v72, v73, v72
	s_waitcnt lgkmcnt(2)
	v_mul_f32_e32 v73, v65, v77
	v_mul_f32_e32 v74, v63, v79
	v_fmac_f32_e32 v73, v60, v76
	v_fmac_f32_e32 v74, v59, v78
	v_add_f32_e32 v72, v69, v72
	v_add_f32_e32 v73, v73, v74
	v_add_f32_e32 v72, v72, v73
	s_waitcnt lgkmcnt(1)
	v_mul_f32_e32 v73, v62, v81
	v_mul_f32_e32 v74, v61, v83
	v_fmac_f32_e32 v73, v58, v80
	v_fmac_f32_e32 v74, v56, v82
	v_add_f32_e32 v73, v73, v74
	v_add_f32_e32 v72, v72, v73
	s_waitcnt lgkmcnt(0)
	v_mul_f32_e32 v73, v57, v85
	v_mul_f32_e32 v74, v55, v87
	v_fmac_f32_e32 v73, v54, v84
	v_fmac_f32_e32 v74, v53, v86
	v_add_f32_e32 v73, v73, v74
	v_add_f32_e32 v72, v72, v73
	v_min_f32_e32 v73, 0, v72
	v_mul_f32_e64 v72, |v72|, s2
	v_exp_f32_e32 v72, v72
	s_nop 0
	v_add_f32_e32 v72, 1.0, v72
	v_cmp_gt_f32_e32 vcc, s22, v72
	s_nop 1
	v_cndmask_b32_e64 v74, 0, 32, vcc
	v_ldexp_f32 v72, v72, v74
	v_log_f32_e32 v72, v72
	s_nop 0
	v_mul_f32_e32 v74, 0x3f317217, v72
	v_fma_f32 v74, v72, s37, -v74
	v_fmac_f32_e32 v74, 0x3377d1cf, v72
	v_fmac_f32_e32 v74, 0x3f317217, v72
	v_cmp_lt_f32_e64 s[38:39], |v72|, s1
	s_nop 1
	v_cndmask_b32_e64 v72, v72, v74, s[38:39]
	v_cndmask_b32_e32 v74, 0, v213, vcc
	v_sub_f32_e32 v72, v72, v74
	v_sub_f32_e32 v72, v73, v72
	v_mul_f32_e32 v72, 0x3d800000, v72
	ds_write_b32 v71, v72
	v_or_b32_e32 v71, 13, v70
	v_lshlrev_b32_e32 v84, 6, v71
	ds_read_b128 v[72:75], v84 offset:16384
	ds_read_b128 v[76:79], v84 offset:16400
	ds_read_b128 v[80:83], v84 offset:16416
	ds_read_b128 v[84:87], v84 offset:16432
	v_lshl_or_b32 v71, v71, 9, v12
	s_waitcnt lgkmcnt(3)
	v_mul_f32_e32 v73, v68, v73
	v_fmac_f32_e32 v73, v66, v72
	v_mul_f32_e32 v72, v67, v75
	v_fmac_f32_e32 v72, v64, v74
	v_add_f32_e32 v72, v73, v72
	s_waitcnt lgkmcnt(2)
	v_mul_f32_e32 v73, v65, v77
	v_mul_f32_e32 v74, v63, v79
	v_fmac_f32_e32 v73, v60, v76
	v_fmac_f32_e32 v74, v59, v78
	v_add_f32_e32 v72, v69, v72
	v_add_f32_e32 v73, v73, v74
	v_add_f32_e32 v72, v72, v73
	s_waitcnt lgkmcnt(1)
	v_mul_f32_e32 v73, v62, v81
	v_mul_f32_e32 v74, v61, v83
	v_fmac_f32_e32 v73, v58, v80
	v_fmac_f32_e32 v74, v56, v82
	v_add_f32_e32 v73, v73, v74
	v_add_f32_e32 v72, v72, v73
	s_waitcnt lgkmcnt(0)
	v_mul_f32_e32 v73, v57, v85
	v_mul_f32_e32 v74, v55, v87
	v_fmac_f32_e32 v73, v54, v84
	v_fmac_f32_e32 v74, v53, v86
	v_add_f32_e32 v73, v73, v74
	v_add_f32_e32 v72, v72, v73
	v_min_f32_e32 v73, 0, v72
	v_mul_f32_e64 v72, |v72|, s2
	v_exp_f32_e32 v72, v72
	v_or_b32_e32 v86, 14, v70
	v_lshlrev_b32_e32 v82, 6, v86
	v_add_f32_e32 v72, 1.0, v72
	v_cmp_gt_f32_e32 vcc, s22, v72
	s_nop 1
	v_cndmask_b32_e64 v74, 0, 32, vcc
	v_ldexp_f32 v72, v72, v74
	v_log_f32_e32 v72, v72
	s_nop 0
	v_mul_f32_e32 v74, 0x3f317217, v72
	v_fma_f32 v74, v72, s37, -v74
	v_fmac_f32_e32 v74, 0x3377d1cf, v72
	v_fmac_f32_e32 v74, 0x3f317217, v72
	v_cmp_lt_f32_e64 s[38:39], |v72|, s1
	s_nop 1
	v_cndmask_b32_e64 v72, v72, v74, s[38:39]
	v_cndmask_b32_e32 v74, 0, v213, vcc
	v_sub_f32_e32 v72, v72, v74
	v_sub_f32_e32 v72, v73, v72
	v_mul_f32_e32 v72, 0x3d800000, v72
	ds_write_b32 v71, v72
	ds_read_b128 v[70:73], v82 offset:16384
	ds_read_b128 v[74:77], v82 offset:16400
	ds_read_b128 v[78:81], v82 offset:16416
	ds_read_b128 v[82:85], v82 offset:16432
	s_waitcnt lgkmcnt(3)
	v_mul_f32_e32 v71, v68, v71
	v_fmac_f32_e32 v71, v66, v70
	v_mul_f32_e32 v70, v67, v73
	v_fmac_f32_e32 v70, v64, v72
	v_add_f32_e32 v70, v71, v70
	s_waitcnt lgkmcnt(2)
	v_mul_f32_e32 v71, v65, v75
	v_mul_f32_e32 v72, v63, v77
	v_fmac_f32_e32 v71, v60, v74
	v_fmac_f32_e32 v72, v59, v76
	v_add_f32_e32 v70, v69, v70
	v_add_f32_e32 v71, v71, v72
	v_add_f32_e32 v70, v70, v71
	s_waitcnt lgkmcnt(1)
	v_mul_f32_e32 v71, v62, v79
	v_mul_f32_e32 v72, v61, v81
	v_fmac_f32_e32 v71, v58, v78
	v_fmac_f32_e32 v72, v56, v80
	v_add_f32_e32 v71, v71, v72
	v_add_f32_e32 v70, v70, v71
	s_waitcnt lgkmcnt(0)
	v_mul_f32_e32 v71, v57, v83
	v_mul_f32_e32 v72, v55, v85
	v_fmac_f32_e32 v71, v54, v82
	v_fmac_f32_e32 v72, v53, v84
	v_add_f32_e32 v71, v71, v72
	v_add_f32_e32 v70, v70, v71
	v_min_f32_e32 v71, 0, v70
	v_mul_f32_e64 v70, |v70|, s2
	v_exp_f32_e32 v70, v70
	v_lshlrev_b32_e32 v82, 6, v13
	v_add_f32_e32 v70, 1.0, v70
	v_cmp_gt_f32_e32 vcc, s22, v70
	s_nop 1
	v_cndmask_b32_e64 v72, 0, 32, vcc
	v_ldexp_f32 v70, v70, v72
	v_log_f32_e32 v70, v70
	s_nop 0
	v_mul_f32_e32 v72, 0x3f317217, v70
	v_fma_f32 v72, v70, s37, -v72
	v_fmac_f32_e32 v72, 0x3377d1cf, v70
	v_fmac_f32_e32 v72, 0x3f317217, v70
	v_cmp_lt_f32_e64 s[38:39], |v70|, s1
	s_nop 1
	v_cndmask_b32_e64 v70, v70, v72, s[38:39]
	v_cndmask_b32_e32 v72, 0, v213, vcc
	v_sub_f32_e32 v70, v70, v72
	v_sub_f32_e32 v70, v71, v70
	v_mul_f32_e32 v70, 0x3d800000, v70
	v_lshl_or_b32 v71, v86, 9, v12
	ds_write_b32 v71, v70
	ds_read_b128 v[70:73], v82 offset:16384
	ds_read_b128 v[74:77], v82 offset:16400
	ds_read_b128 v[78:81], v82 offset:16416
	ds_read_b128 v[82:85], v82 offset:16432
	v_lshl_or_b32 v12, v13, 9, v12
	s_waitcnt lgkmcnt(3)
	v_mul_f32_e32 v68, v68, v71
	s_waitcnt lgkmcnt(2)
	v_mul_f32_e32 v65, v65, v75
	v_fmac_f32_e32 v65, v60, v74
	v_mul_f32_e32 v60, v63, v77
	v_fmac_f32_e32 v68, v66, v70
	v_mul_f32_e32 v66, v67, v73
	v_fmac_f32_e32 v60, v59, v76
	v_fmac_f32_e32 v66, v64, v72
	v_add_f32_e32 v59, v65, v60
	s_waitcnt lgkmcnt(1)
	v_mul_f32_e32 v60, v62, v79
	v_add_f32_e32 v64, v68, v66
	v_fmac_f32_e32 v60, v58, v78
	v_mul_f32_e32 v58, v61, v81
	s_waitcnt lgkmcnt(0)
	v_mul_f32_e32 v57, v57, v83
	v_add_f32_e32 v64, v69, v64
	v_fmac_f32_e32 v58, v56, v80
	v_fmac_f32_e32 v57, v54, v82
	v_mul_f32_e32 v54, v55, v85
	v_add_f32_e32 v59, v64, v59
	v_add_f32_e32 v56, v60, v58
	v_fmac_f32_e32 v54, v53, v84
	v_add_f32_e32 v56, v59, v56
	v_add_f32_e32 v53, v57, v54
	v_add_f32_e32 v53, v56, v53
	v_min_f32_e32 v54, 0, v53
	v_mul_f32_e64 v53, |v53|, s2
	v_exp_f32_e32 v53, v53
	s_movk_i32 s2, 0x80
	v_add_f32_e32 v53, 1.0, v53
	v_cmp_gt_f32_e32 vcc, s22, v53
	s_nop 1
	v_cndmask_b32_e64 v55, 0, 32, vcc
	v_ldexp_f32 v53, v53, v55
	v_log_f32_e32 v53, v53
	s_nop 0
	v_mul_f32_e32 v55, 0x3f317217, v53
	v_fma_f32 v55, v53, s37, -v55
	v_fmac_f32_e32 v55, 0x3377d1cf, v53
	v_fmac_f32_e32 v55, 0x3f317217, v53
	v_cmp_lt_f32_e64 s[38:39], |v53|, s1
	s_nop 1
	v_cndmask_b32_e64 v53, v53, v55, s[38:39]
	v_cndmask_b32_e32 v55, 0, v213, vcc
	v_sub_f32_e32 v53, v53, v55
	v_sub_f32_e32 v53, v54, v53
	v_mul_f32_e32 v53, 0x3d800000, v53
	v_cmp_gt_i32_e32 vcc, s2, v52
	ds_write_b32 v12, v53
	s_waitcnt lgkmcnt(0)
	s_barrier
	s_and_saveexec_b64 s[2:3], vcc
	s_cbranch_execz .LBB0_474
	ds_read2st64_b32 v[216:217], v9 offset1:2
	ds_read2st64_b32 v[218:219], v9 offset0:4 offset1:6
	ds_read2st64_b32 v[220:221], v9 offset0:8 offset1:10
	ds_read2st64_b32 v[222:223], v9 offset0:12 offset1:14
	ds_read2st64_b32 v[224:225], v9 offset0:16 offset1:18
	ds_read2st64_b32 v[226:227], v9 offset0:20 offset1:22
	ds_read2st64_b32 v[228:229], v9 offset0:24 offset1:26
	ds_read2st64_b32 v[230:231], v9 offset0:28 offset1:30
	ds_read2st64_b32 v[232:233], v9 offset0:32 offset1:34
	ds_read2st64_b32 v[234:235], v9 offset0:36 offset1:38
	ds_read2st64_b32 v[236:237], v9 offset0:40 offset1:42
	ds_read2st64_b32 v[238:239], v9 offset0:44 offset1:46
	ds_read2st64_b32 v[240:241], v9 offset0:48 offset1:50
	ds_read2st64_b32 v[242:243], v9 offset0:52 offset1:54
	ds_read2st64_b32 v[244:245], v9 offset0:56 offset1:58
	ds_read2st64_b32 v[246:247], v9 offset0:60 offset1:62
	s_waitcnt lgkmcnt(15)
	v_add_f32_e32 v12, 0, v216
	v_add_f32_e32 v52, v12, v217
	ds_write2st64_b32 v9, v12, v52 offset1:2
	s_waitcnt lgkmcnt(15)
	v_add_f32_e32 v12, v52, v218
	v_add_f32_e32 v52, v12, v219
	ds_write2st64_b32 v9, v12, v52 offset0:4 offset1:6
	s_waitcnt lgkmcnt(15)
	v_add_f32_e32 v12, v52, v220
	v_add_f32_e32 v52, v12, v221
	ds_write2st64_b32 v9, v12, v52 offset0:8 offset1:10
	s_waitcnt lgkmcnt(15)
	v_add_f32_e32 v12, v52, v222
	v_add_f32_e32 v52, v12, v223
	ds_write2st64_b32 v9, v12, v52 offset0:12 offset1:14
	s_waitcnt lgkmcnt(15)
	v_add_f32_e32 v12, v52, v224
	v_add_f32_e32 v52, v12, v225
	ds_write2st64_b32 v9, v12, v52 offset0:16 offset1:18
	s_waitcnt lgkmcnt(15)
	v_add_f32_e32 v12, v52, v226
	v_add_f32_e32 v52, v12, v227
	ds_write2st64_b32 v9, v12, v52 offset0:20 offset1:22
	s_waitcnt lgkmcnt(15)
	v_add_f32_e32 v12, v52, v228
	v_add_f32_e32 v52, v12, v229
	ds_write2st64_b32 v9, v12, v52 offset0:24 offset1:26
	s_waitcnt lgkmcnt(15)
	v_add_f32_e32 v12, v52, v230
	v_add_f32_e32 v52, v12, v231
	ds_write2st64_b32 v9, v12, v52 offset0:28 offset1:30
	s_waitcnt lgkmcnt(15)
	v_add_f32_e32 v12, v52, v232
	v_add_f32_e32 v52, v12, v233
	ds_write2st64_b32 v9, v12, v52 offset0:32 offset1:34
	s_waitcnt lgkmcnt(15)
	v_add_f32_e32 v12, v52, v234
	v_add_f32_e32 v52, v12, v235
	ds_write2st64_b32 v9, v12, v52 offset0:36 offset1:38
	s_waitcnt lgkmcnt(15)
	v_add_f32_e32 v12, v52, v236
	v_add_f32_e32 v52, v12, v237
	ds_write2st64_b32 v9, v12, v52 offset0:40 offset1:42
	s_waitcnt lgkmcnt(15)
	v_add_f32_e32 v12, v52, v238
	v_add_f32_e32 v52, v12, v239
	ds_write2st64_b32 v9, v12, v52 offset0:44 offset1:46
	s_waitcnt lgkmcnt(15)
	v_add_f32_e32 v12, v52, v240
	v_add_f32_e32 v52, v12, v241
	ds_write2st64_b32 v9, v12, v52 offset0:48 offset1:50
	s_waitcnt lgkmcnt(15)
	v_add_f32_e32 v12, v52, v242
	v_add_f32_e32 v52, v12, v243
	ds_write2st64_b32 v9, v12, v52 offset0:52 offset1:54
	s_waitcnt lgkmcnt(15)
	v_add_f32_e32 v12, v52, v244
	v_add_f32_e32 v52, v12, v245
	ds_write2st64_b32 v9, v12, v52 offset0:56 offset1:58
	s_waitcnt lgkmcnt(15)
	v_add_f32_e32 v12, v52, v246
	v_add_f32_e32 v13, v12, v247
	ds_write2st64_b32 v9, v12, v13 offset0:60 offset1:62
